# sc1 write-through stores for G1 and G3 epilogues
# speedup vs baseline: 1.0291x; 1.0291x over previous
; __device__ __forceinline__ unsigned cvt_pk(float lo, float hi) { unsigned r; asm volatile("v_cvt_pk_bf16_f32 %0, %1, %2" : "=v"(r) : "v"(lo), "v"(hi)); return r; }
; __device__ __forceinline__ float silu(float x) { return x * sigm(x); }
;     __device__ __forceinline__ void operator()(const f32x4 (&acc)[2][2][4][2], const Unit& u, int wr, int wc, int fr, int fq) const {
;         const int row0 = u.pm * BM + wr * 64 + fr, col0 = u.pn * BM + wc * 32 + 8 * fq; const bool gate = u.pn >= 6;
; #pragma unroll
;         for (int ai = 0; ai < 2; ++ai)
; #pragma unroll
;             for (int m = 0; m < 4; ++m) { bf16_t* rowp = O + (size_t)(row0 + ai * HALF + m * 16) * LDP + col0;
; #pragma unroll
;                 for (int bj = 0; bj < 2; ++bj) { f32x4 v0 = acc[ai][bj][m][0], v1 = acc[ai][bj][m][1];
;                     if (gate) {
; #pragma unroll
;                         for (int e = 0; e < 4; ++e) { v0[e] = silu(v0[e]); v1[e] = silu(v1[e]); } }
;                     u32x4 w; w.x = cvt_pk(v0[0], v0[1]); w.y = cvt_pk(v0[2], v0[3]); w.z = cvt_pk(v1[0], v1[1]); w.w = cvt_pk(v1[2], v1[3]);
;                     *(u32x4*)(rowp + bj * HALF) = w; } }
.LBB0_391:
	v_lshl_or_b32 v128, s39, 8, v157
	v_cvt_pk_bf16_f32 v124, v124, v125
	v_cvt_pk_bf16_f32 v125, v126, v127
	v_cvt_pk_bf16_f32 v126, v120, v121
	v_cndmask_b32_e64 v120, 0, 1, s[14:15]
	v_lshl_add_u64 v[154:155], v[128:129], 1, v[138:139]
	v_cmp_ne_u32_e64 s[4:5], 1, v120
	s_andn2_b64 vcc, exec, s[14:15]
	v_cvt_pk_bf16_f32 v127, v122, v123
	global_store_dwordx4 v[154:155], v[124:127], off sc1
	s_cbranch_vccnz .LBB0_393
	v_mul_f32_e32 v121, 0xbfb8aa3b, v112
	v_mul_f32_e32 v122, 0xbfb8aa3b, v117
	v_exp_f32_e32 v121, v121
	v_exp_f32_e32 v123, v122
	v_mul_f32_e32 v125, 0xbfb8aa3b, v114
	v_mul_f32_e32 v126, 0xbfb8aa3b, v119
	v_add_f32_e32 v121, 1.0, v121
	v_mul_f32_e32 v120, 0xbfb8aa3b, v116
	v_rcp_f32_e32 v122, v121
	v_add_f32_e32 v121, 1.0, v123
	v_mul_f32_e32 v123, 0xbfb8aa3b, v113
	v_mul_f32_e32 v124, 0xbfb8aa3b, v118
	v_exp_f32_e32 v125, v125
	v_exp_f32_e32 v127, v126
	v_mul_f32_e32 v126, 0xbfb8aa3b, v115
	v_exp_f32_e32 v120, v120
	v_exp_f32_e32 v123, v123
	v_exp_f32_e32 v124, v124
	v_exp_f32_e32 v162, v126
	v_add_f32_e32 v125, 1.0, v125
	v_add_f32_e32 v120, 1.0, v120
	v_add_f32_e32 v123, 1.0, v123
	v_add_f32_e32 v124, 1.0, v124
	v_rcp_f32_e32 v126, v125
	v_add_f32_e32 v125, 1.0, v127
	v_add_f32_e32 v127, 1.0, v162
	v_rcp_f32_e32 v120, v120
	v_rcp_f32_e32 v121, v121
	v_rcp_f32_e32 v124, v124
	v_rcp_f32_e32 v125, v125
	v_rcp_f32_e32 v127, v127
	v_rcp_f32_e32 v123, v123
	v_pk_mul_f32 v[116:117], v[116:117], v[120:121]
	v_pk_mul_f32 v[118:119], v[118:119], v[124:125]
	v_pk_mul_f32 v[114:115], v[114:115], v[126:127]
	v_pk_mul_f32 v[112:113], v[112:113], v[122:123]
.LBB0_393:
	s_and_b64 vcc, exec, s[4:5]
	v_cvt_pk_bf16_f32 v116, v116, v117
	v_cvt_pk_bf16_f32 v117, v118, v119
	v_cvt_pk_bf16_f32 v118, v112, v113
	v_cvt_pk_bf16_f32 v119, v114, v115
	global_store_dwordx4 v[154:155], v[116:119], off offset:256 sc1
	s_cbranch_vccnz .LBB0_395
	v_mul_f32_e32 v113, 0xbfb8aa3b, v104
	v_mul_f32_e32 v114, 0xbfb8aa3b, v109
	v_exp_f32_e32 v113, v113
	v_exp_f32_e32 v115, v114
	v_mul_f32_e32 v117, 0xbfb8aa3b, v106
	v_mul_f32_e32 v118, 0xbfb8aa3b, v111
	v_add_f32_e32 v113, 1.0, v113
	v_mul_f32_e32 v112, 0xbfb8aa3b, v108
	v_rcp_f32_e32 v114, v113
	v_add_f32_e32 v113, 1.0, v115
	v_mul_f32_e32 v115, 0xbfb8aa3b, v105
	v_mul_f32_e32 v116, 0xbfb8aa3b, v110
	v_exp_f32_e32 v117, v117
	v_exp_f32_e32 v119, v118
	v_mul_f32_e32 v118, 0xbfb8aa3b, v107
	v_exp_f32_e32 v112, v112
	v_exp_f32_e32 v115, v115
	v_exp_f32_e32 v116, v116
	v_exp_f32_e32 v120, v118
	v_add_f32_e32 v117, 1.0, v117
	v_add_f32_e32 v112, 1.0, v112
	v_add_f32_e32 v115, 1.0, v115
	v_add_f32_e32 v116, 1.0, v116
	v_rcp_f32_e32 v118, v117
	v_add_f32_e32 v117, 1.0, v119
	v_add_f32_e32 v119, 1.0, v120
	v_rcp_f32_e32 v112, v112
	v_rcp_f32_e32 v113, v113
	v_rcp_f32_e32 v116, v116
	v_rcp_f32_e32 v117, v117
	v_rcp_f32_e32 v119, v119
	v_rcp_f32_e32 v115, v115
	v_pk_mul_f32 v[108:109], v[108:109], v[112:113]
	v_pk_mul_f32 v[110:111], v[110:111], v[116:117]
	v_pk_mul_f32 v[106:107], v[106:107], v[118:119]
	v_pk_mul_f32 v[104:105], v[104:105], v[114:115]
.LBB0_395:
	v_lshl_add_u64 v[112:113], v[128:129], 1, v[140:141]
	s_and_b64 vcc, exec, s[4:5]
	v_cvt_pk_bf16_f32 v108, v108, v109
	v_cvt_pk_bf16_f32 v109, v110, v111
	v_cvt_pk_bf16_f32 v110, v104, v105
	v_cvt_pk_bf16_f32 v111, v106, v107
	global_store_dwordx4 v[112:113], v[108:111], off sc1
	s_cbranch_vccnz .LBB0_397
	v_mul_f32_e32 v105, 0xbfb8aa3b, v96
	v_mul_f32_e32 v106, 0xbfb8aa3b, v101
	v_exp_f32_e32 v105, v105
	v_exp_f32_e32 v107, v106
	v_mul_f32_e32 v109, 0xbfb8aa3b, v98
	v_mul_f32_e32 v110, 0xbfb8aa3b, v103
	v_add_f32_e32 v105, 1.0, v105
	v_mul_f32_e32 v104, 0xbfb8aa3b, v100
	v_rcp_f32_e32 v106, v105
	v_add_f32_e32 v105, 1.0, v107
	v_mul_f32_e32 v107, 0xbfb8aa3b, v97
	v_mul_f32_e32 v108, 0xbfb8aa3b, v102
	v_exp_f32_e32 v109, v109
	v_exp_f32_e32 v111, v110
	v_mul_f32_e32 v110, 0xbfb8aa3b, v99
	v_exp_f32_e32 v104, v104
	v_exp_f32_e32 v107, v107
	v_exp_f32_e32 v108, v108
	v_exp_f32_e32 v114, v110
	v_add_f32_e32 v109, 1.0, v109
	v_add_f32_e32 v104, 1.0, v104
	v_add_f32_e32 v107, 1.0, v107
	v_add_f32_e32 v108, 1.0, v108
	v_rcp_f32_e32 v110, v109
	v_add_f32_e32 v109, 1.0, v111
	v_add_f32_e32 v111, 1.0, v114
	v_rcp_f32_e32 v104, v104
	v_rcp_f32_e32 v105, v105
	v_rcp_f32_e32 v108, v108
	v_rcp_f32_e32 v109, v109
	v_rcp_f32_e32 v111, v111
	v_rcp_f32_e32 v107, v107
	v_pk_mul_f32 v[100:101], v[100:101], v[104:105]
	v_pk_mul_f32 v[102:103], v[102:103], v[108:109]
	v_pk_mul_f32 v[98:99], v[98:99], v[110:111]
	v_pk_mul_f32 v[96:97], v[96:97], v[106:107]
.LBB0_397:
	s_and_b64 vcc, exec, s[4:5]
	v_cvt_pk_bf16_f32 v100, v100, v101
	v_cvt_pk_bf16_f32 v101, v102, v103
	v_cvt_pk_bf16_f32 v102, v96, v97
	v_cvt_pk_bf16_f32 v103, v98, v99
	global_store_dwordx4 v[112:113], v[100:103], off offset:256 sc1
	s_cbranch_vccnz .LBB0_399
	v_mul_f32_e32 v97, 0xbfb8aa3b, v88
	v_mul_f32_e32 v98, 0xbfb8aa3b, v93
	v_exp_f32_e32 v97, v97
	v_exp_f32_e32 v99, v98
	v_mul_f32_e32 v101, 0xbfb8aa3b, v90
	v_mul_f32_e32 v102, 0xbfb8aa3b, v95
	v_add_f32_e32 v97, 1.0, v97
	v_mul_f32_e32 v96, 0xbfb8aa3b, v92
	v_rcp_f32_e32 v98, v97
	v_add_f32_e32 v97, 1.0, v99
	v_mul_f32_e32 v99, 0xbfb8aa3b, v89
	v_mul_f32_e32 v100, 0xbfb8aa3b, v94
	v_exp_f32_e32 v101, v101
	v_exp_f32_e32 v103, v102
	v_mul_f32_e32 v102, 0xbfb8aa3b, v91
	v_exp_f32_e32 v96, v96
	v_exp_f32_e32 v99, v99
	v_exp_f32_e32 v100, v100
	v_exp_f32_e32 v104, v102
	v_add_f32_e32 v101, 1.0, v101
	v_add_f32_e32 v96, 1.0, v96
	v_add_f32_e32 v99, 1.0, v99
	v_add_f32_e32 v100, 1.0, v100
	v_rcp_f32_e32 v102, v101
	v_add_f32_e32 v101, 1.0, v103
	v_add_f32_e32 v103, 1.0, v104
	v_rcp_f32_e32 v96, v96
	v_rcp_f32_e32 v97, v97
	v_rcp_f32_e32 v100, v100
	v_rcp_f32_e32 v101, v101
	v_rcp_f32_e32 v103, v103
	v_rcp_f32_e32 v99, v99
	v_pk_mul_f32 v[92:93], v[92:93], v[96:97]
	v_pk_mul_f32 v[94:95], v[94:95], v[100:101]
	v_pk_mul_f32 v[90:91], v[90:91], v[102:103]
	v_pk_mul_f32 v[88:89], v[88:89], v[98:99]
; __device__ __forceinline__ unsigned cvt_pk(float lo, float hi) { unsigned r; asm volatile("v_cvt_pk_bf16_f32 %0, %1, %2" : "=v"(r) : "v"(lo), "v"(hi)); return r; }
; __device__ __forceinline__ float silu(float x) { return x * sigm(x); }
;     __device__ __forceinline__ void operator()(const f32x4 (&acc)[2][2][4][2], const Unit& u, int wr, int wc, int fr, int fq) const {
;         const int row0 = u.pm * BM + wr * 64 + fr, col0 = u.pn * BM + wc * 32 + 8 * fq; const bool gate = u.pn >= 6;
; #pragma unroll
;         for (int ai = 0; ai < 2; ++ai)
; #pragma unroll
;             for (int m = 0; m < 4; ++m) { bf16_t* rowp = O + (size_t)(row0 + ai * HALF + m * 16) * LDP + col0;
; #pragma unroll
;                 for (int bj = 0; bj < 2; ++bj) { f32x4 v0 = acc[ai][bj][m][0], v1 = acc[ai][bj][m][1];
;                     if (gate) {
; #pragma unroll
;                         for (int e = 0; e < 4; ++e) { v0[e] = silu(v0[e]); v1[e] = silu(v1[e]); } }
;                     u32x4 w; w.x = cvt_pk(v0[0], v0[1]); w.y = cvt_pk(v0[2], v0[3]); w.z = cvt_pk(v1[0], v1[1]); w.w = cvt_pk(v1[2], v1[3]);
;                     *(u32x4*)(rowp + bj * HALF) = w; } }
.LBB0_399:
	v_lshl_add_u64 v[96:97], v[128:129], 1, v[142:143]
	s_and_b64 vcc, exec, s[4:5]
	v_cvt_pk_bf16_f32 v92, v92, v93
	v_cvt_pk_bf16_f32 v93, v94, v95
	v_cvt_pk_bf16_f32 v94, v88, v89
	v_cvt_pk_bf16_f32 v95, v90, v91
	global_store_dwordx4 v[96:97], v[92:95], off sc1
	s_cbranch_vccnz .LBB0_401
	v_mul_f32_e32 v89, 0xbfb8aa3b, v80
	v_mul_f32_e32 v90, 0xbfb8aa3b, v85
	v_exp_f32_e32 v89, v89
	v_exp_f32_e32 v91, v90
	v_mul_f32_e32 v93, 0xbfb8aa3b, v82
	v_mul_f32_e32 v94, 0xbfb8aa3b, v87
	v_add_f32_e32 v89, 1.0, v89
	v_mul_f32_e32 v88, 0xbfb8aa3b, v84
	v_rcp_f32_e32 v90, v89
	v_add_f32_e32 v89, 1.0, v91
	v_mul_f32_e32 v91, 0xbfb8aa3b, v81
	v_mul_f32_e32 v92, 0xbfb8aa3b, v86
	v_exp_f32_e32 v93, v93
	v_exp_f32_e32 v95, v94
	v_mul_f32_e32 v94, 0xbfb8aa3b, v83
	v_exp_f32_e32 v88, v88
	v_exp_f32_e32 v91, v91
	v_exp_f32_e32 v92, v92
	v_exp_f32_e32 v98, v94
	v_add_f32_e32 v93, 1.0, v93
	v_add_f32_e32 v88, 1.0, v88
	v_add_f32_e32 v91, 1.0, v91
	v_add_f32_e32 v92, 1.0, v92
	v_rcp_f32_e32 v94, v93
	v_add_f32_e32 v93, 1.0, v95
	v_add_f32_e32 v95, 1.0, v98
	v_rcp_f32_e32 v88, v88
	v_rcp_f32_e32 v89, v89
	v_rcp_f32_e32 v92, v92
	v_rcp_f32_e32 v93, v93
	v_rcp_f32_e32 v95, v95
	v_rcp_f32_e32 v91, v91
	v_pk_mul_f32 v[84:85], v[84:85], v[88:89]
	v_pk_mul_f32 v[86:87], v[86:87], v[92:93]
	v_pk_mul_f32 v[82:83], v[82:83], v[94:95]
	v_pk_mul_f32 v[80:81], v[80:81], v[90:91]
.LBB0_401:
	s_and_b64 vcc, exec, s[4:5]
	v_cvt_pk_bf16_f32 v84, v84, v85
	v_cvt_pk_bf16_f32 v85, v86, v87
	v_cvt_pk_bf16_f32 v86, v80, v81
	v_cvt_pk_bf16_f32 v87, v82, v83
	global_store_dwordx4 v[96:97], v[84:87], off offset:256 sc1
	s_cbranch_vccnz .LBB0_403
	v_mul_f32_e32 v81, 0xbfb8aa3b, v72
	v_mul_f32_e32 v82, 0xbfb8aa3b, v77
	v_exp_f32_e32 v81, v81
	v_exp_f32_e32 v83, v82
	v_mul_f32_e32 v85, 0xbfb8aa3b, v74
	v_mul_f32_e32 v86, 0xbfb8aa3b, v79
	v_add_f32_e32 v81, 1.0, v81
	v_mul_f32_e32 v80, 0xbfb8aa3b, v76
	v_rcp_f32_e32 v82, v81
	v_add_f32_e32 v81, 1.0, v83
	v_mul_f32_e32 v83, 0xbfb8aa3b, v73
	v_mul_f32_e32 v84, 0xbfb8aa3b, v78
	v_exp_f32_e32 v85, v85
	v_exp_f32_e32 v87, v86
	v_mul_f32_e32 v86, 0xbfb8aa3b, v75
	v_exp_f32_e32 v80, v80
	v_exp_f32_e32 v83, v83
	v_exp_f32_e32 v84, v84
	v_exp_f32_e32 v88, v86
	v_add_f32_e32 v85, 1.0, v85
	v_add_f32_e32 v80, 1.0, v80
	v_add_f32_e32 v83, 1.0, v83
	v_add_f32_e32 v84, 1.0, v84
	v_rcp_f32_e32 v86, v85
	v_add_f32_e32 v85, 1.0, v87
	v_add_f32_e32 v87, 1.0, v88
	v_rcp_f32_e32 v80, v80
	v_rcp_f32_e32 v81, v81
	v_rcp_f32_e32 v84, v84
	v_rcp_f32_e32 v85, v85
	v_rcp_f32_e32 v87, v87
	v_rcp_f32_e32 v83, v83
	v_pk_mul_f32 v[76:77], v[76:77], v[80:81]
	v_pk_mul_f32 v[78:79], v[78:79], v[84:85]
	v_pk_mul_f32 v[74:75], v[74:75], v[86:87]
	v_pk_mul_f32 v[72:73], v[72:73], v[82:83]
.LBB0_403:
	v_lshl_add_u64 v[80:81], v[128:129], 1, v[144:145]
	s_and_b64 vcc, exec, s[4:5]
	v_cvt_pk_bf16_f32 v76, v76, v77
	v_cvt_pk_bf16_f32 v77, v78, v79
	v_cvt_pk_bf16_f32 v78, v72, v73
	v_cvt_pk_bf16_f32 v79, v74, v75
	global_store_dwordx4 v[80:81], v[76:79], off sc1
	s_cbranch_vccnz .LBB0_405
	v_mul_f32_e32 v73, 0xbfb8aa3b, v64
	v_mul_f32_e32 v74, 0xbfb8aa3b, v69
	v_exp_f32_e32 v73, v73
	v_exp_f32_e32 v75, v74
	v_mul_f32_e32 v77, 0xbfb8aa3b, v66
	v_mul_f32_e32 v78, 0xbfb8aa3b, v71
	v_add_f32_e32 v73, 1.0, v73
	v_mul_f32_e32 v72, 0xbfb8aa3b, v68
	v_rcp_f32_e32 v74, v73
	v_add_f32_e32 v73, 1.0, v75
	v_mul_f32_e32 v75, 0xbfb8aa3b, v65
	v_mul_f32_e32 v76, 0xbfb8aa3b, v70
	v_exp_f32_e32 v77, v77
	v_exp_f32_e32 v79, v78
	v_mul_f32_e32 v78, 0xbfb8aa3b, v67
	v_exp_f32_e32 v72, v72
	v_exp_f32_e32 v75, v75
	v_exp_f32_e32 v76, v76
	v_exp_f32_e32 v82, v78
	v_add_f32_e32 v77, 1.0, v77
	v_add_f32_e32 v72, 1.0, v72
	v_add_f32_e32 v75, 1.0, v75
	v_add_f32_e32 v76, 1.0, v76
	v_rcp_f32_e32 v78, v77
	v_add_f32_e32 v77, 1.0, v79
	v_add_f32_e32 v79, 1.0, v82
	v_rcp_f32_e32 v72, v72
	v_rcp_f32_e32 v73, v73
	v_rcp_f32_e32 v76, v76
	v_rcp_f32_e32 v77, v77
	v_rcp_f32_e32 v79, v79
	v_rcp_f32_e32 v75, v75
	v_pk_mul_f32 v[68:69], v[68:69], v[72:73]
	v_pk_mul_f32 v[70:71], v[70:71], v[76:77]
	v_pk_mul_f32 v[66:67], v[66:67], v[78:79]
	v_pk_mul_f32 v[64:65], v[64:65], v[74:75]
.LBB0_405:
	s_and_b64 vcc, exec, s[4:5]
	v_cvt_pk_bf16_f32 v68, v68, v69
	v_cvt_pk_bf16_f32 v69, v70, v71
	v_cvt_pk_bf16_f32 v70, v64, v65
	v_cvt_pk_bf16_f32 v71, v66, v67
	global_store_dwordx4 v[80:81], v[68:71], off offset:256 sc1
	s_cbranch_vccnz .LBB0_407
	v_mul_f32_e32 v65, 0xbfb8aa3b, v56
	v_mul_f32_e32 v66, 0xbfb8aa3b, v61
	v_exp_f32_e32 v65, v65
	v_exp_f32_e32 v67, v66
	v_mul_f32_e32 v69, 0xbfb8aa3b, v58
	v_mul_f32_e32 v70, 0xbfb8aa3b, v63
	v_add_f32_e32 v65, 1.0, v65
	v_mul_f32_e32 v64, 0xbfb8aa3b, v60
	v_rcp_f32_e32 v66, v65
	v_add_f32_e32 v65, 1.0, v67
	v_mul_f32_e32 v67, 0xbfb8aa3b, v57
	v_mul_f32_e32 v68, 0xbfb8aa3b, v62
	v_exp_f32_e32 v69, v69
	v_exp_f32_e32 v71, v70
	v_mul_f32_e32 v70, 0xbfb8aa3b, v59
	v_exp_f32_e32 v64, v64
	v_exp_f32_e32 v67, v67
	v_exp_f32_e32 v68, v68
	v_exp_f32_e32 v72, v70
	v_add_f32_e32 v69, 1.0, v69
	v_add_f32_e32 v64, 1.0, v64
	v_add_f32_e32 v67, 1.0, v67
	v_add_f32_e32 v68, 1.0, v68
	v_rcp_f32_e32 v70, v69
	v_add_f32_e32 v69, 1.0, v71
	v_add_f32_e32 v71, 1.0, v72
	v_rcp_f32_e32 v64, v64
	v_rcp_f32_e32 v65, v65
	v_rcp_f32_e32 v68, v68
	v_rcp_f32_e32 v69, v69
	v_rcp_f32_e32 v71, v71
	v_rcp_f32_e32 v67, v67
	v_pk_mul_f32 v[60:61], v[60:61], v[64:65]
	v_pk_mul_f32 v[62:63], v[62:63], v[68:69]
	v_pk_mul_f32 v[58:59], v[58:59], v[70:71]
	v_pk_mul_f32 v[56:57], v[56:57], v[66:67]
; __device__ __forceinline__ unsigned cvt_pk(float lo, float hi) { unsigned r; asm volatile("v_cvt_pk_bf16_f32 %0, %1, %2" : "=v"(r) : "v"(lo), "v"(hi)); return r; }
; __device__ __forceinline__ float silu(float x) { return x * sigm(x); }
;     __device__ __forceinline__ void operator()(const f32x4 (&acc)[2][2][4][2], const Unit& u, int wr, int wc, int fr, int fq) const {
;         const int row0 = u.pm * BM + wr * 64 + fr, col0 = u.pn * BM + wc * 32 + 8 * fq; const bool gate = u.pn >= 6;
; #pragma unroll
;         for (int ai = 0; ai < 2; ++ai)
; #pragma unroll
;             for (int m = 0; m < 4; ++m) { bf16_t* rowp = O + (size_t)(row0 + ai * HALF + m * 16) * LDP + col0;
; #pragma unroll
;                 for (int bj = 0; bj < 2; ++bj) { f32x4 v0 = acc[ai][bj][m][0], v1 = acc[ai][bj][m][1];
;                     if (gate) {
; #pragma unroll
;                         for (int e = 0; e < 4; ++e) { v0[e] = silu(v0[e]); v1[e] = silu(v1[e]); } }
;                     u32x4 w; w.x = cvt_pk(v0[0], v0[1]); w.y = cvt_pk(v0[2], v0[3]); w.z = cvt_pk(v1[0], v1[1]); w.w = cvt_pk(v1[2], v1[3]);
;                     *(u32x4*)(rowp + bj * HALF) = w; } }
.LBB0_407:
	v_lshl_add_u64 v[64:65], v[128:129], 1, v[146:147]
	s_and_b64 vcc, exec, s[4:5]
	v_cvt_pk_bf16_f32 v60, v60, v61
	v_cvt_pk_bf16_f32 v61, v62, v63
	v_cvt_pk_bf16_f32 v62, v56, v57
	v_cvt_pk_bf16_f32 v63, v58, v59
	global_store_dwordx4 v[64:65], v[60:63], off sc1
	s_cbranch_vccnz .LBB0_409
	v_mul_f32_e32 v57, 0xbfb8aa3b, v48
	v_mul_f32_e32 v58, 0xbfb8aa3b, v53
	v_exp_f32_e32 v57, v57
	v_exp_f32_e32 v59, v58
	v_mul_f32_e32 v61, 0xbfb8aa3b, v50
	v_mul_f32_e32 v62, 0xbfb8aa3b, v55
	v_add_f32_e32 v57, 1.0, v57
	v_mul_f32_e32 v56, 0xbfb8aa3b, v52
	v_rcp_f32_e32 v58, v57
	v_add_f32_e32 v57, 1.0, v59
	v_mul_f32_e32 v59, 0xbfb8aa3b, v49
	v_mul_f32_e32 v60, 0xbfb8aa3b, v54
	v_exp_f32_e32 v61, v61
	v_exp_f32_e32 v63, v62
	v_mul_f32_e32 v62, 0xbfb8aa3b, v51
	v_exp_f32_e32 v56, v56
	v_exp_f32_e32 v59, v59
	v_exp_f32_e32 v60, v60
	v_exp_f32_e32 v66, v62
	v_add_f32_e32 v61, 1.0, v61
	v_add_f32_e32 v56, 1.0, v56
	v_add_f32_e32 v59, 1.0, v59
	v_add_f32_e32 v60, 1.0, v60
	v_rcp_f32_e32 v62, v61
	v_add_f32_e32 v61, 1.0, v63
	v_add_f32_e32 v63, 1.0, v66
	v_rcp_f32_e32 v56, v56
	v_rcp_f32_e32 v57, v57
	v_rcp_f32_e32 v60, v60
	v_rcp_f32_e32 v61, v61
	v_rcp_f32_e32 v63, v63
	v_rcp_f32_e32 v59, v59
	v_pk_mul_f32 v[52:53], v[52:53], v[56:57]
	v_pk_mul_f32 v[54:55], v[54:55], v[60:61]
	v_pk_mul_f32 v[50:51], v[50:51], v[62:63]
	v_pk_mul_f32 v[48:49], v[48:49], v[58:59]
.LBB0_409:
	s_and_b64 vcc, exec, s[4:5]
	v_cvt_pk_bf16_f32 v52, v52, v53
	v_cvt_pk_bf16_f32 v53, v54, v55
	v_cvt_pk_bf16_f32 v54, v48, v49
	v_cvt_pk_bf16_f32 v55, v50, v51
	global_store_dwordx4 v[64:65], v[52:55], off offset:256 sc1
	s_cbranch_vccnz .LBB0_411
	v_mul_f32_e32 v49, 0xbfb8aa3b, v40
	v_mul_f32_e32 v50, 0xbfb8aa3b, v45
	v_exp_f32_e32 v49, v49
	v_exp_f32_e32 v51, v50
	v_mul_f32_e32 v53, 0xbfb8aa3b, v42
	v_mul_f32_e32 v54, 0xbfb8aa3b, v47
	v_add_f32_e32 v49, 1.0, v49
	v_mul_f32_e32 v48, 0xbfb8aa3b, v44
	v_rcp_f32_e32 v50, v49
	v_add_f32_e32 v49, 1.0, v51
	v_mul_f32_e32 v51, 0xbfb8aa3b, v41
	v_mul_f32_e32 v52, 0xbfb8aa3b, v46
	v_exp_f32_e32 v53, v53
	v_exp_f32_e32 v55, v54
	v_mul_f32_e32 v54, 0xbfb8aa3b, v43
	v_exp_f32_e32 v48, v48
	v_exp_f32_e32 v51, v51
	v_exp_f32_e32 v52, v52
	v_exp_f32_e32 v56, v54
	v_add_f32_e32 v53, 1.0, v53
	v_add_f32_e32 v48, 1.0, v48
	v_add_f32_e32 v51, 1.0, v51
	v_add_f32_e32 v52, 1.0, v52
	v_rcp_f32_e32 v54, v53
	v_add_f32_e32 v53, 1.0, v55
	v_add_f32_e32 v55, 1.0, v56
	v_rcp_f32_e32 v48, v48
	v_rcp_f32_e32 v49, v49
	v_rcp_f32_e32 v52, v52
	v_rcp_f32_e32 v53, v53
	v_rcp_f32_e32 v55, v55
	v_rcp_f32_e32 v51, v51
	v_pk_mul_f32 v[44:45], v[44:45], v[48:49]
	v_pk_mul_f32 v[46:47], v[46:47], v[52:53]
	v_pk_mul_f32 v[42:43], v[42:43], v[54:55]
	v_pk_mul_f32 v[40:41], v[40:41], v[50:51]
.LBB0_411:
	v_lshl_add_u64 v[48:49], v[128:129], 1, v[148:149]
	s_and_b64 vcc, exec, s[4:5]
	v_cvt_pk_bf16_f32 v44, v44, v45
	v_cvt_pk_bf16_f32 v45, v46, v47
	v_cvt_pk_bf16_f32 v46, v40, v41
	v_cvt_pk_bf16_f32 v47, v42, v43
	global_store_dwordx4 v[48:49], v[44:47], off sc1
	s_cbranch_vccnz .LBB0_413
	v_mul_f32_e32 v41, 0xbfb8aa3b, v32
	v_mul_f32_e32 v42, 0xbfb8aa3b, v37
	v_exp_f32_e32 v41, v41
	v_exp_f32_e32 v43, v42
	v_mul_f32_e32 v45, 0xbfb8aa3b, v34
	v_mul_f32_e32 v46, 0xbfb8aa3b, v39
	v_add_f32_e32 v41, 1.0, v41
	v_mul_f32_e32 v40, 0xbfb8aa3b, v36
	v_rcp_f32_e32 v42, v41
	v_add_f32_e32 v41, 1.0, v43
	v_mul_f32_e32 v43, 0xbfb8aa3b, v33
	v_mul_f32_e32 v44, 0xbfb8aa3b, v38
	v_exp_f32_e32 v45, v45
	v_exp_f32_e32 v47, v46
	v_mul_f32_e32 v46, 0xbfb8aa3b, v35
	v_exp_f32_e32 v40, v40
	v_exp_f32_e32 v43, v43
	v_exp_f32_e32 v44, v44
	v_exp_f32_e32 v50, v46
	v_add_f32_e32 v45, 1.0, v45
	v_add_f32_e32 v40, 1.0, v40
	v_add_f32_e32 v43, 1.0, v43
	v_add_f32_e32 v44, 1.0, v44
	v_rcp_f32_e32 v46, v45
	v_add_f32_e32 v45, 1.0, v47
	v_add_f32_e32 v47, 1.0, v50
	v_rcp_f32_e32 v40, v40
	v_rcp_f32_e32 v41, v41
	v_rcp_f32_e32 v44, v44
	v_rcp_f32_e32 v45, v45
	v_rcp_f32_e32 v47, v47
	v_rcp_f32_e32 v43, v43
	v_pk_mul_f32 v[36:37], v[36:37], v[40:41]
	v_pk_mul_f32 v[38:39], v[38:39], v[44:45]
	v_pk_mul_f32 v[34:35], v[34:35], v[46:47]
	v_pk_mul_f32 v[32:33], v[32:33], v[42:43]
; __device__ __forceinline__ unsigned cvt_pk(float lo, float hi) { unsigned r; asm volatile("v_cvt_pk_bf16_f32 %0, %1, %2" : "=v"(r) : "v"(lo), "v"(hi)); return r; }
; __device__ __forceinline__ float silu(float x) { return x * sigm(x); }
;     __device__ __forceinline__ void operator()(const f32x4 (&acc)[2][2][4][2], const Unit& u, int wr, int wc, int fr, int fq) const {
;         const int row0 = u.pm * BM + wr * 64 + fr, col0 = u.pn * BM + wc * 32 + 8 * fq; const bool gate = u.pn >= 6;
; #pragma unroll
;         for (int ai = 0; ai < 2; ++ai)
; #pragma unroll
;             for (int m = 0; m < 4; ++m) { bf16_t* rowp = O + (size_t)(row0 + ai * HALF + m * 16) * LDP + col0;
; #pragma unroll
;                 for (int bj = 0; bj < 2; ++bj) { f32x4 v0 = acc[ai][bj][m][0], v1 = acc[ai][bj][m][1];
;                     if (gate) {
; #pragma unroll
;                         for (int e = 0; e < 4; ++e) { v0[e] = silu(v0[e]); v1[e] = silu(v1[e]); } }
;                     u32x4 w; w.x = cvt_pk(v0[0], v0[1]); w.y = cvt_pk(v0[2], v0[3]); w.z = cvt_pk(v1[0], v1[1]); w.w = cvt_pk(v1[2], v1[3]);
;                     *(u32x4*)(rowp + bj * HALF) = w; } }
.LBB0_413:
	s_and_b64 vcc, exec, s[4:5]
	v_cvt_pk_bf16_f32 v36, v36, v37
	v_cvt_pk_bf16_f32 v37, v38, v39
	v_cvt_pk_bf16_f32 v38, v32, v33
	v_cvt_pk_bf16_f32 v39, v34, v35
	global_store_dwordx4 v[48:49], v[36:39], off offset:256 sc1
	s_cbranch_vccnz .LBB0_415
	v_mul_f32_e32 v33, 0xbfb8aa3b, v24
	v_mul_f32_e32 v34, 0xbfb8aa3b, v29
	v_exp_f32_e32 v33, v33
	v_exp_f32_e32 v35, v34
	v_mul_f32_e32 v37, 0xbfb8aa3b, v26
	v_mul_f32_e32 v38, 0xbfb8aa3b, v31
	v_add_f32_e32 v33, 1.0, v33
	v_mul_f32_e32 v32, 0xbfb8aa3b, v28
	v_rcp_f32_e32 v34, v33
	v_add_f32_e32 v33, 1.0, v35
	v_mul_f32_e32 v35, 0xbfb8aa3b, v25
	v_mul_f32_e32 v36, 0xbfb8aa3b, v30
	v_exp_f32_e32 v37, v37
	v_exp_f32_e32 v39, v38
	v_mul_f32_e32 v38, 0xbfb8aa3b, v27
	v_exp_f32_e32 v32, v32
	v_exp_f32_e32 v35, v35
	v_exp_f32_e32 v36, v36
	v_exp_f32_e32 v40, v38
	v_add_f32_e32 v37, 1.0, v37
	v_add_f32_e32 v32, 1.0, v32
	v_add_f32_e32 v35, 1.0, v35
	v_add_f32_e32 v36, 1.0, v36
	v_rcp_f32_e32 v38, v37
	v_add_f32_e32 v37, 1.0, v39
	v_add_f32_e32 v39, 1.0, v40
	v_rcp_f32_e32 v32, v32
	v_rcp_f32_e32 v33, v33
	v_rcp_f32_e32 v36, v36
	v_rcp_f32_e32 v37, v37
	v_rcp_f32_e32 v39, v39
	v_rcp_f32_e32 v35, v35
	v_pk_mul_f32 v[28:29], v[28:29], v[32:33]
	v_pk_mul_f32 v[30:31], v[30:31], v[36:37]
	v_pk_mul_f32 v[26:27], v[26:27], v[38:39]
	v_pk_mul_f32 v[24:25], v[24:25], v[34:35]
.LBB0_415:
	v_lshl_add_u64 v[32:33], v[128:129], 1, v[150:151]
	s_and_b64 vcc, exec, s[4:5]
	v_cvt_pk_bf16_f32 v28, v28, v29
	v_cvt_pk_bf16_f32 v29, v30, v31
	v_cvt_pk_bf16_f32 v30, v24, v25
	v_cvt_pk_bf16_f32 v31, v26, v27
	global_store_dwordx4 v[32:33], v[28:31], off sc1
	s_cbranch_vccnz .LBB0_417
	v_mul_f32_e32 v25, 0xbfb8aa3b, v16
	v_mul_f32_e32 v26, 0xbfb8aa3b, v21
	v_exp_f32_e32 v25, v25
	v_exp_f32_e32 v27, v26
	v_mul_f32_e32 v29, 0xbfb8aa3b, v18
	v_mul_f32_e32 v30, 0xbfb8aa3b, v23
	v_add_f32_e32 v25, 1.0, v25
	v_mul_f32_e32 v24, 0xbfb8aa3b, v20
	v_rcp_f32_e32 v26, v25
	v_add_f32_e32 v25, 1.0, v27
	v_mul_f32_e32 v27, 0xbfb8aa3b, v17
	v_mul_f32_e32 v28, 0xbfb8aa3b, v22
	v_exp_f32_e32 v29, v29
	v_exp_f32_e32 v31, v30
	v_mul_f32_e32 v30, 0xbfb8aa3b, v19
	v_exp_f32_e32 v24, v24
	v_exp_f32_e32 v27, v27
	v_exp_f32_e32 v28, v28
	v_exp_f32_e32 v34, v30
	v_add_f32_e32 v29, 1.0, v29
	v_add_f32_e32 v24, 1.0, v24
	v_add_f32_e32 v27, 1.0, v27
	v_add_f32_e32 v28, 1.0, v28
	v_rcp_f32_e32 v30, v29
	v_add_f32_e32 v29, 1.0, v31
	v_add_f32_e32 v31, 1.0, v34
	v_rcp_f32_e32 v24, v24
	v_rcp_f32_e32 v25, v25
	v_rcp_f32_e32 v28, v28
	v_rcp_f32_e32 v29, v29
	v_rcp_f32_e32 v31, v31
	v_rcp_f32_e32 v27, v27
	v_pk_mul_f32 v[20:21], v[20:21], v[24:25]
	v_pk_mul_f32 v[22:23], v[22:23], v[28:29]
	v_pk_mul_f32 v[18:19], v[18:19], v[30:31]
	v_pk_mul_f32 v[16:17], v[16:17], v[26:27]
.LBB0_417:
	s_and_b64 vcc, exec, s[4:5]
	v_cvt_pk_bf16_f32 v20, v20, v21
	v_cvt_pk_bf16_f32 v21, v22, v23
	v_cvt_pk_bf16_f32 v22, v16, v17
	v_cvt_pk_bf16_f32 v23, v18, v19
	global_store_dwordx4 v[32:33], v[20:23], off offset:256 sc1
	s_cbranch_vccnz .LBB0_419
	v_mul_f32_e32 v17, 0xbfb8aa3b, v8
	v_mul_f32_e32 v18, 0xbfb8aa3b, v13
	v_exp_f32_e32 v17, v17
	v_exp_f32_e32 v19, v18
	v_mul_f32_e32 v21, 0xbfb8aa3b, v10
	v_mul_f32_e32 v22, 0xbfb8aa3b, v15
	v_add_f32_e32 v17, 1.0, v17
	v_mul_f32_e32 v16, 0xbfb8aa3b, v12
	v_rcp_f32_e32 v18, v17
	v_add_f32_e32 v17, 1.0, v19
	v_mul_f32_e32 v19, 0xbfb8aa3b, v9
	v_mul_f32_e32 v20, 0xbfb8aa3b, v14
	v_exp_f32_e32 v21, v21
	v_exp_f32_e32 v23, v22
	v_mul_f32_e32 v22, 0xbfb8aa3b, v11
	v_exp_f32_e32 v16, v16
	v_exp_f32_e32 v19, v19
	v_exp_f32_e32 v20, v20
	v_exp_f32_e32 v24, v22
	v_add_f32_e32 v21, 1.0, v21
	v_add_f32_e32 v16, 1.0, v16
	v_add_f32_e32 v19, 1.0, v19
	v_add_f32_e32 v20, 1.0, v20
	v_rcp_f32_e32 v22, v21
	v_add_f32_e32 v21, 1.0, v23
	v_add_f32_e32 v23, 1.0, v24
	v_rcp_f32_e32 v16, v16
	v_rcp_f32_e32 v17, v17
	v_rcp_f32_e32 v20, v20
	v_rcp_f32_e32 v21, v21
	v_rcp_f32_e32 v23, v23
	v_rcp_f32_e32 v19, v19
	v_pk_mul_f32 v[12:13], v[12:13], v[16:17]
	v_pk_mul_f32 v[14:15], v[14:15], v[20:21]
	v_pk_mul_f32 v[10:11], v[10:11], v[22:23]
	v_pk_mul_f32 v[8:9], v[8:9], v[18:19]
.LBB0_419:
	v_lshl_add_u64 v[16:17], v[128:129], 1, v[152:153]
	s_and_b64 vcc, exec, s[4:5]
	v_cvt_pk_bf16_f32 v12, v12, v13
	v_cvt_pk_bf16_f32 v13, v14, v15
	v_cvt_pk_bf16_f32 v14, v8, v9
	v_cvt_pk_bf16_f32 v15, v10, v11
	global_store_dwordx4 v[16:17], v[12:15], off sc1
	s_cbranch_vccnz .LBB0_386
	v_mul_f32_e32 v9, 0xbfb8aa3b, v0
	v_mul_f32_e32 v10, 0xbfb8aa3b, v5
	v_exp_f32_e32 v9, v9
	v_exp_f32_e32 v11, v10
	v_mul_f32_e32 v13, 0xbfb8aa3b, v2
	v_mul_f32_e32 v14, 0xbfb8aa3b, v7
	v_add_f32_e32 v9, 1.0, v9
	v_mul_f32_e32 v8, 0xbfb8aa3b, v4
	v_rcp_f32_e32 v10, v9
	v_add_f32_e32 v9, 1.0, v11
	v_mul_f32_e32 v11, 0xbfb8aa3b, v1
	v_mul_f32_e32 v12, 0xbfb8aa3b, v6
	v_exp_f32_e32 v13, v13
	v_exp_f32_e32 v15, v14
	v_mul_f32_e32 v14, 0xbfb8aa3b, v3
	v_exp_f32_e32 v8, v8
	v_exp_f32_e32 v11, v11
	v_exp_f32_e32 v12, v12
	v_exp_f32_e32 v18, v14
	v_add_f32_e32 v13, 1.0, v13
	v_add_f32_e32 v8, 1.0, v8
	v_add_f32_e32 v11, 1.0, v11
	v_add_f32_e32 v12, 1.0, v12
	v_rcp_f32_e32 v14, v13
	v_add_f32_e32 v13, 1.0, v15
	v_add_f32_e32 v15, 1.0, v18
	v_rcp_f32_e32 v8, v8
	v_rcp_f32_e32 v9, v9
	v_rcp_f32_e32 v12, v12
	v_rcp_f32_e32 v13, v13
	v_rcp_f32_e32 v15, v15
	v_rcp_f32_e32 v11, v11
	v_pk_mul_f32 v[4:5], v[4:5], v[8:9]
	v_pk_mul_f32 v[6:7], v[6:7], v[12:13]
	v_pk_mul_f32 v[2:3], v[2:3], v[14:15]
	v_pk_mul_f32 v[0:1], v[0:1], v[10:11]
	s_branch .LBB0_386
